# non-temporal (nt) stores for the FFN hidden activations written by the gate/up GEMM epilogue
# speedup vs baseline: 1.0079x; 1.0005x over previous
.LBB0_1290:
	v_mov_b32_e32 v142, v138
	v_mov_b32_e32 v143, v139
	v_pk_mul_f32 v[118:119], v[118:119], v[114:115]
	v_lshlrev_b32_e32 v144, 3, v143
	v_exp_f32_e32 v143, v120
	v_exp_f32_e32 v114, v114
	v_exp_f32_e32 v115, v115
	v_pk_mul_f32 v[126:127], v[126:127], v[122:123]
	v_add_f32_e32 v143, 1.0, v143
	v_rcp_f32_e32 v146, v143
	v_exp_f32_e32 v143, v121
	v_pk_mul_f32 v[120:121], v[124:125], v[120:121]
	v_exp_f32_e32 v124, v112
	v_exp_f32_e32 v125, v113
	v_exp_f32_e32 v122, v122
	v_exp_f32_e32 v123, v123
	v_add_f32_e32 v124, 1.0, v124
	v_add_f32_e32 v125, 1.0, v125
	v_rcp_f32_e32 v124, v124
	v_rcp_f32_e32 v125, v125
	v_add_f32_e32 v114, 1.0, v114
	v_add_f32_e32 v115, 1.0, v115
	v_rcp_f32_e32 v114, v114
	v_rcp_f32_e32 v115, v115
	s_lshl_b32 s0, s0, 8
	v_add_f32_e32 v143, 1.0, v143
	s_add_i32 s0, s0, s71
	v_rcp_f32_e32 v147, v143
	v_add_f32_e32 v122, 1.0, v122
	v_add_f32_e32 v123, 1.0, v123
	v_pk_mul_f32 v[112:113], v[116:117], v[112:113]
	v_add_u32_e32 v142, s0, v142
	s_lshl_b32 s0, s1, 7
	v_rcp_f32_e32 v122, v122
	v_rcp_f32_e32 v123, v123
	v_pk_mul_f32 v[112:113], v[112:113], v[124:125]
	s_ashr_i32 s1, s0, 31
	v_pk_mul_f32 v[114:115], v[118:119], v[114:115]
	v_cvt_pk_bf16_f32 v118, v112, v113
	v_mov_b64_e32 v[112:113], s[38:39]
	v_cvt_pk_bf16_f32 v119, v114, v115
	v_mad_i64_i32 v[114:115], s[2:3], v142, s80, v[112:113]
	s_lshl_b64 s[0:1], s[0:1], 1
	v_ashrrev_i32_e32 v145, 31, v144
	v_pk_mul_f32 v[120:121], v[120:121], v[146:147]
	v_lshl_add_u64 v[114:115], v[114:115], 0, s[0:1]
	s_mov_b32 s47, s56
	v_pk_mul_f32 v[122:123], v[126:127], v[122:123]
	v_cvt_pk_bf16_f32 v116, v120, v121
	v_lshl_add_u64 v[120:121], v[114:115], 0, s[46:47]
	v_lshlrev_b64 v[114:115], 1, v[144:145]
	v_cvt_pk_bf16_f32 v117, v122, v123
	v_lshl_add_u64 v[120:121], v[120:121], 0, v[114:115]
	global_store_dwordx4 v[120:121], v[116:119], off nt
	v_pk_mul_f32 v[110:111], v[110:111], v[106:107]
	v_exp_f32_e32 v106, v106
	v_exp_f32_e32 v116, v104
	v_exp_f32_e32 v117, v105
	v_pk_mul_f32 v[104:105], v[108:109], v[104:105]
	v_exp_f32_e32 v108, v96
	v_exp_f32_e32 v109, v97
	v_pk_mul_f32 v[96:97], v[100:101], v[96:97]
	v_exp_f32_e32 v107, v107
	v_add_f32_e32 v108, 1.0, v108
	v_add_f32_e32 v109, 1.0, v109
	v_rcp_f32_e32 v108, v108
	v_rcp_f32_e32 v109, v109
	v_add_f32_e32 v116, 1.0, v116
	v_add_f32_e32 v117, 1.0, v117
	v_add_f32_e32 v106, 1.0, v106
	v_pk_mul_f32 v[100:101], v[96:97], v[108:109]
	v_exp_f32_e32 v96, v98
	v_exp_f32_e32 v97, v99
	v_add_f32_e32 v107, 1.0, v107
	v_rcp_f32_e32 v116, v116
	v_add_f32_e32 v96, 1.0, v96
	v_add_f32_e32 v97, 1.0, v97
	v_rcp_f32_e32 v117, v117
	v_rcp_f32_e32 v106, v106
	v_rcp_f32_e32 v107, v107
	v_rcp_f32_e32 v96, v96
	v_rcp_f32_e32 v97, v97
	v_add_u32_e32 v118, 16, v142
	v_pk_mul_f32 v[102:103], v[102:103], v[98:99]
	v_cvt_pk_bf16_f32 v98, v100, v101
	v_mad_i64_i32 v[100:101], s[2:3], v118, s80, v[112:113]
	v_lshl_add_u64 v[100:101], v[100:101], 0, s[0:1]
	v_pk_mul_f32 v[104:105], v[104:105], v[116:117]
	v_pk_mul_f32 v[106:107], v[110:111], v[106:107]
	v_pk_mul_f32 v[102:103], v[102:103], v[96:97]
	v_lshl_add_u64 v[100:101], v[100:101], 0, s[46:47]
	v_cvt_pk_bf16_f32 v96, v104, v105
	v_cvt_pk_bf16_f32 v97, v106, v107
	v_cvt_pk_bf16_f32 v99, v102, v103
	v_lshl_add_u64 v[100:101], v[100:101], 0, v[114:115]
	global_store_dwordx4 v[100:101], v[96:99], off nt
	v_pk_mul_f32 v[94:95], v[94:95], v[90:91]
	v_exp_f32_e32 v90, v90
	v_exp_f32_e32 v96, v88
	v_exp_f32_e32 v97, v89
	v_pk_mul_f32 v[88:89], v[92:93], v[88:89]
	v_exp_f32_e32 v92, v80
	v_exp_f32_e32 v93, v81
	v_pk_mul_f32 v[80:81], v[84:85], v[80:81]
	v_exp_f32_e32 v91, v91
	v_add_f32_e32 v92, 1.0, v92
	v_add_f32_e32 v93, 1.0, v93
	v_rcp_f32_e32 v92, v92
	v_rcp_f32_e32 v93, v93
	v_add_f32_e32 v96, 1.0, v96
	v_add_f32_e32 v97, 1.0, v97
	v_add_f32_e32 v90, 1.0, v90
	v_pk_mul_f32 v[84:85], v[80:81], v[92:93]
	v_exp_f32_e32 v80, v82
	v_exp_f32_e32 v81, v83
	v_add_f32_e32 v91, 1.0, v91
	v_rcp_f32_e32 v96, v96
	v_add_f32_e32 v80, 1.0, v80
	v_add_f32_e32 v81, 1.0, v81
	v_rcp_f32_e32 v97, v97
	v_rcp_f32_e32 v90, v90
	v_rcp_f32_e32 v91, v91
	v_rcp_f32_e32 v80, v80
	v_rcp_f32_e32 v81, v81
	v_add_u32_e32 v98, 32, v142
	v_pk_mul_f32 v[86:87], v[86:87], v[82:83]
	v_cvt_pk_bf16_f32 v82, v84, v85
	v_mad_i64_i32 v[84:85], s[2:3], v98, s80, v[112:113]
	v_lshl_add_u64 v[84:85], v[84:85], 0, s[0:1]
	v_pk_mul_f32 v[88:89], v[88:89], v[96:97]
	v_pk_mul_f32 v[90:91], v[94:95], v[90:91]
	v_pk_mul_f32 v[86:87], v[86:87], v[80:81]
	v_lshl_add_u64 v[84:85], v[84:85], 0, s[46:47]
	v_cvt_pk_bf16_f32 v80, v88, v89
	v_cvt_pk_bf16_f32 v81, v90, v91
	v_cvt_pk_bf16_f32 v83, v86, v87
	v_lshl_add_u64 v[84:85], v[84:85], 0, v[114:115]
	global_store_dwordx4 v[84:85], v[80:83], off nt
	v_pk_mul_f32 v[78:79], v[78:79], v[74:75]
	v_exp_f32_e32 v74, v74
	v_exp_f32_e32 v80, v72
	v_exp_f32_e32 v81, v73
	v_pk_mul_f32 v[72:73], v[76:77], v[72:73]
	v_exp_f32_e32 v76, v64
	v_exp_f32_e32 v77, v65
	v_pk_mul_f32 v[64:65], v[68:69], v[64:65]
	v_exp_f32_e32 v75, v75
	v_add_f32_e32 v76, 1.0, v76
	v_add_f32_e32 v77, 1.0, v77
	v_rcp_f32_e32 v76, v76
	v_rcp_f32_e32 v77, v77
	v_add_f32_e32 v80, 1.0, v80
	v_add_f32_e32 v81, 1.0, v81
	v_add_f32_e32 v74, 1.0, v74
	v_pk_mul_f32 v[68:69], v[64:65], v[76:77]
	v_exp_f32_e32 v64, v66
	v_exp_f32_e32 v65, v67
	v_add_f32_e32 v75, 1.0, v75
	v_rcp_f32_e32 v80, v80
	v_add_f32_e32 v64, 1.0, v64
	v_add_f32_e32 v65, 1.0, v65
	v_rcp_f32_e32 v81, v81
	v_rcp_f32_e32 v74, v74
	v_rcp_f32_e32 v75, v75
	v_rcp_f32_e32 v64, v64
	v_rcp_f32_e32 v65, v65
	v_add_u32_e32 v82, 48, v142
	v_pk_mul_f32 v[70:71], v[70:71], v[66:67]
	v_cvt_pk_bf16_f32 v66, v68, v69
	v_mad_i64_i32 v[68:69], s[2:3], v82, s80, v[112:113]
	v_lshl_add_u64 v[68:69], v[68:69], 0, s[0:1]
	v_pk_mul_f32 v[72:73], v[72:73], v[80:81]
	v_pk_mul_f32 v[74:75], v[78:79], v[74:75]
	v_pk_mul_f32 v[70:71], v[70:71], v[64:65]
	v_lshl_add_u64 v[68:69], v[68:69], 0, s[46:47]
	v_cvt_pk_bf16_f32 v64, v72, v73
	v_cvt_pk_bf16_f32 v65, v74, v75
	v_cvt_pk_bf16_f32 v67, v70, v71
	v_lshl_add_u64 v[68:69], v[68:69], 0, v[114:115]
	global_store_dwordx4 v[68:69], v[64:67], off nt
	v_pk_mul_f32 v[62:63], v[62:63], v[58:59]
	v_exp_f32_e32 v58, v58
	v_exp_f32_e32 v64, v56
	v_exp_f32_e32 v65, v57
	v_pk_mul_f32 v[56:57], v[60:61], v[56:57]
	v_exp_f32_e32 v60, v48
	v_exp_f32_e32 v61, v49
	v_pk_mul_f32 v[48:49], v[52:53], v[48:49]
	v_exp_f32_e32 v59, v59
	v_add_f32_e32 v60, 1.0, v60
	v_add_f32_e32 v61, 1.0, v61
	v_rcp_f32_e32 v60, v60
	v_rcp_f32_e32 v61, v61
	v_add_f32_e32 v64, 1.0, v64
	v_add_f32_e32 v65, 1.0, v65
	v_add_f32_e32 v58, 1.0, v58
	v_pk_mul_f32 v[52:53], v[48:49], v[60:61]
	v_exp_f32_e32 v48, v50
	v_exp_f32_e32 v49, v51
	v_add_f32_e32 v59, 1.0, v59
	v_rcp_f32_e32 v64, v64
	v_add_f32_e32 v48, 1.0, v48
	v_add_f32_e32 v49, 1.0, v49
	v_rcp_f32_e32 v65, v65
	v_rcp_f32_e32 v58, v58
	v_rcp_f32_e32 v59, v59
	v_rcp_f32_e32 v48, v48
	v_rcp_f32_e32 v49, v49
	v_add_u32_e32 v66, 0x80, v142
	v_pk_mul_f32 v[54:55], v[54:55], v[50:51]
	v_cvt_pk_bf16_f32 v50, v52, v53
	v_mad_i64_i32 v[52:53], s[2:3], v66, s80, v[112:113]
	v_lshl_add_u64 v[52:53], v[52:53], 0, s[0:1]
	v_pk_mul_f32 v[56:57], v[56:57], v[64:65]
	v_pk_mul_f32 v[58:59], v[62:63], v[58:59]
	v_pk_mul_f32 v[54:55], v[54:55], v[48:49]
	v_lshl_add_u64 v[52:53], v[52:53], 0, s[46:47]
	v_cvt_pk_bf16_f32 v48, v56, v57
	v_cvt_pk_bf16_f32 v49, v58, v59
	v_cvt_pk_bf16_f32 v51, v54, v55
	v_lshl_add_u64 v[52:53], v[52:53], 0, v[114:115]
	global_store_dwordx4 v[52:53], v[48:51], off nt
	v_pk_mul_f32 v[46:47], v[46:47], v[42:43]
	v_exp_f32_e32 v42, v42
	v_exp_f32_e32 v48, v40
	v_exp_f32_e32 v49, v41
	v_pk_mul_f32 v[40:41], v[44:45], v[40:41]
	v_exp_f32_e32 v44, v32
	v_exp_f32_e32 v45, v33
	v_pk_mul_f32 v[32:33], v[36:37], v[32:33]
	v_exp_f32_e32 v43, v43
	v_add_f32_e32 v44, 1.0, v44
	v_add_f32_e32 v45, 1.0, v45
	v_rcp_f32_e32 v44, v44
	v_rcp_f32_e32 v45, v45
	v_add_f32_e32 v48, 1.0, v48
	v_add_f32_e32 v49, 1.0, v49
	v_add_f32_e32 v42, 1.0, v42
	v_pk_mul_f32 v[36:37], v[32:33], v[44:45]
	v_exp_f32_e32 v32, v34
	v_exp_f32_e32 v33, v35
	v_add_f32_e32 v43, 1.0, v43
	v_rcp_f32_e32 v48, v48
	v_add_f32_e32 v32, 1.0, v32
	v_add_f32_e32 v33, 1.0, v33
	v_rcp_f32_e32 v49, v49
	v_rcp_f32_e32 v42, v42
	v_rcp_f32_e32 v43, v43
	v_rcp_f32_e32 v32, v32
	v_rcp_f32_e32 v33, v33
	v_add_u32_e32 v50, 0x90, v142
	v_pk_mul_f32 v[38:39], v[38:39], v[34:35]
	v_cvt_pk_bf16_f32 v34, v36, v37
	v_mad_i64_i32 v[36:37], s[2:3], v50, s80, v[112:113]
	v_lshl_add_u64 v[36:37], v[36:37], 0, s[0:1]
	v_pk_mul_f32 v[40:41], v[40:41], v[48:49]
	v_pk_mul_f32 v[42:43], v[46:47], v[42:43]
	v_pk_mul_f32 v[38:39], v[38:39], v[32:33]
	v_lshl_add_u64 v[36:37], v[36:37], 0, s[46:47]
	v_cvt_pk_bf16_f32 v32, v40, v41
	v_cvt_pk_bf16_f32 v33, v42, v43
	v_cvt_pk_bf16_f32 v35, v38, v39
	v_lshl_add_u64 v[36:37], v[36:37], 0, v[114:115]
	global_store_dwordx4 v[36:37], v[32:35], off nt
	v_pk_mul_f32 v[30:31], v[30:31], v[26:27]
	v_exp_f32_e32 v26, v26
	v_exp_f32_e32 v32, v24
	v_exp_f32_e32 v33, v25
	v_pk_mul_f32 v[24:25], v[28:29], v[24:25]
	v_exp_f32_e32 v28, v16
	v_exp_f32_e32 v29, v17
	v_pk_mul_f32 v[16:17], v[20:21], v[16:17]
	v_exp_f32_e32 v27, v27
	v_add_f32_e32 v28, 1.0, v28
	v_add_f32_e32 v29, 1.0, v29
	v_rcp_f32_e32 v28, v28
	v_rcp_f32_e32 v29, v29
	v_add_f32_e32 v32, 1.0, v32
	v_add_f32_e32 v33, 1.0, v33
	v_add_f32_e32 v26, 1.0, v26
	v_pk_mul_f32 v[20:21], v[16:17], v[28:29]
	v_exp_f32_e32 v16, v18
	v_exp_f32_e32 v17, v19
	v_add_f32_e32 v27, 1.0, v27
	v_rcp_f32_e32 v32, v32
	v_add_f32_e32 v16, 1.0, v16
	v_add_f32_e32 v17, 1.0, v17
	v_rcp_f32_e32 v33, v33
	v_rcp_f32_e32 v26, v26
	v_rcp_f32_e32 v27, v27
	v_rcp_f32_e32 v16, v16
	v_rcp_f32_e32 v17, v17
	v_add_u32_e32 v34, 0xa0, v142
	v_pk_mul_f32 v[22:23], v[22:23], v[18:19]
	v_cvt_pk_bf16_f32 v18, v20, v21
	v_mad_i64_i32 v[20:21], s[2:3], v34, s80, v[112:113]
	v_lshl_add_u64 v[20:21], v[20:21], 0, s[0:1]
	v_pk_mul_f32 v[24:25], v[24:25], v[32:33]
	v_pk_mul_f32 v[26:27], v[30:31], v[26:27]
	v_pk_mul_f32 v[22:23], v[22:23], v[16:17]
	v_lshl_add_u64 v[20:21], v[20:21], 0, s[46:47]
	v_cvt_pk_bf16_f32 v16, v24, v25
	v_cvt_pk_bf16_f32 v17, v26, v27
	v_cvt_pk_bf16_f32 v19, v22, v23
	v_lshl_add_u64 v[20:21], v[20:21], 0, v[114:115]
	global_store_dwordx4 v[20:21], v[16:19], off nt
	v_pk_mul_f32 v[14:15], v[14:15], v[10:11]
	v_exp_f32_e32 v10, v10
	v_exp_f32_e32 v16, v8
	v_exp_f32_e32 v17, v9
	v_pk_mul_f32 v[8:9], v[12:13], v[8:9]
	v_exp_f32_e32 v12, v0
	v_exp_f32_e32 v13, v1
	v_pk_mul_f32 v[0:1], v[4:5], v[0:1]
	v_exp_f32_e32 v11, v11
	v_add_f32_e32 v12, 1.0, v12
	v_add_f32_e32 v13, 1.0, v13
	v_rcp_f32_e32 v12, v12
	v_rcp_f32_e32 v13, v13
	v_add_f32_e32 v16, 1.0, v16
	v_add_f32_e32 v17, 1.0, v17
	v_add_f32_e32 v10, 1.0, v10
	v_pk_mul_f32 v[4:5], v[0:1], v[12:13]
	v_exp_f32_e32 v0, v2
	v_exp_f32_e32 v1, v3
	v_add_f32_e32 v11, 1.0, v11
	v_rcp_f32_e32 v16, v16
	v_add_f32_e32 v0, 1.0, v0
	v_add_f32_e32 v1, 1.0, v1
	v_rcp_f32_e32 v17, v17
	v_rcp_f32_e32 v10, v10
	v_rcp_f32_e32 v11, v11
	v_rcp_f32_e32 v0, v0
	v_rcp_f32_e32 v1, v1
	v_add_u32_e32 v18, 0xb0, v142
	v_pk_mul_f32 v[6:7], v[6:7], v[2:3]
	v_cvt_pk_bf16_f32 v2, v4, v5
	v_mad_i64_i32 v[4:5], s[2:3], v18, s80, v[112:113]
	v_lshl_add_u64 v[4:5], v[4:5], 0, s[0:1]
	v_pk_mul_f32 v[8:9], v[8:9], v[16:17]
	v_pk_mul_f32 v[10:11], v[14:15], v[10:11]
	v_pk_mul_f32 v[6:7], v[6:7], v[0:1]
	v_lshl_add_u64 v[4:5], v[4:5], 0, s[46:47]
	v_cvt_pk_bf16_f32 v0, v8, v9
	v_cvt_pk_bf16_f32 v1, v10, v11
	v_cvt_pk_bf16_f32 v3, v6, v7
	v_lshl_add_u64 v[4:5], v[4:5], 0, v[114:115]
	s_mov_b64 s[0:1], -1
	s_andn2_b64 vcc, exec, s[40:41]
	global_store_dwordx4 v[4:5], v[0:3], off nt
	s_cbranch_vccnz .LBB0_1282
	s_andn2_b64 vcc, exec, s[22:23]
	s_cbranch_vccnz .LBB0_1281
	s_barrier
	s_branch .LBB0_1281
